# phase_init: the 4 chunk loads of each row issued together
# baseline (speedup 1.0000x reference)
; DI uint32_t pack2(float a, float b) { f2_t v = {a, b}; bf2_t r = __builtin_convertvector(v, bf2_t); return __builtin_bit_cast(uint32_t, r); }
; DI void phase_init(const Params& p) {
;     ...
;   for (int row = gw; row < NTOK; row += nw) {
;     const float* xr = p.x + (size_t)row * 1024;
;     float ss = 0.f;
; #pragma unroll
;     for (int i = 0; i < 4; ++i) {
;       float4 v = *(const float4*)(xr + i * 256 + lane * 4);
;       ss += v.x * v.x + v.y * v.y + v.z * v.z + v.w * v.w;
;       *(uint2*)(XB + (size_t)row * LDX + i * 256 + lane * 4) = make_uint2(pack2(v.x, v.y), pack2(v.z, v.w));
;     }
; #pragma unroll
;     for (int off = 32; off >= 1; off >>= 1) ss += __shfl_xor(ss, off);
;     if (lane < 16) XSS[(size_t)row * 16 + lane] = (lane == 0) ? ss : 0.f;
;   }
.LBB0_1469:
	s_waitcnt lgkmcnt(0)
	global_load_dwordx4 v[14:17], v[0:1], off
	global_load_dwordx4 v[96:99], v[0:1], off offset:1024
	global_load_dwordx4 v[100:103], v[0:1], off offset:2048
	global_load_dwordx4 v[104:107], v[0:1], off offset:3072
	v_lshl_add_u64 v[18:19], s[94:95], 0, v[4:5]
	v_add_co_u32_e32 v30, vcc, s43, v18
	s_waitcnt vmcnt(3)
	v_cvt_pk_bf16_f32 v18, v14, v15
	v_addc_co_u32_e32 v31, vcc, 0, v19, vcc
	v_cvt_pk_bf16_f32 v19, v16, v17
	global_store_dwordx2 v[30:31], v[18:19], off
	v_pk_mul_f32 v[14:15], v[14:15], v[14:15]
	v_pk_mul_f32 v[16:17], v[16:17], v[16:17]
	v_add_f32_e32 v14, v14, v15
	v_add_f32_e32 v14, v14, v16
	v_add_f32_e32 v32, v14, v17
	s_waitcnt vmcnt(3)
	v_mov_b64_e32 v[18:19], v[96:97]
	v_mov_b64_e32 v[20:21], v[98:99]
	v_cvt_pk_bf16_f32 v22, v18, v19
	v_cvt_pk_bf16_f32 v23, v20, v21
	global_store_dwordx2 v[30:31], v[22:23], off offset:512
	v_pk_mul_f32 v[14:15], v[18:19], v[18:19]
	v_pk_mul_f32 v[16:17], v[20:21], v[20:21]
	v_add_f32_e32 v14, v14, v15
	v_add_f32_e32 v14, v14, v16
	v_add_f32_e32 v14, v14, v17
	v_add_f32_e32 v18, v32, v14
	s_waitcnt vmcnt(3)
	v_mov_b64_e32 v[22:23], v[100:101]
	v_mov_b64_e32 v[24:25], v[102:103]
	v_cvt_pk_bf16_f32 v26, v22, v23
	v_cvt_pk_bf16_f32 v27, v24, v25
	global_store_dwordx2 v[30:31], v[26:27], off offset:1024
	v_pk_mul_f32 v[14:15], v[22:23], v[22:23]
	v_pk_mul_f32 v[16:17], v[24:25], v[24:25]
	v_add_f32_e32 v14, v14, v15
	v_add_f32_e32 v14, v14, v16
	v_add_f32_e32 v19, v14, v17
	v_add_f32_e32 v18, v18, v19
	s_waitcnt vmcnt(3)
	v_mov_b64_e32 v[26:27], v[104:105]
	v_mov_b64_e32 v[28:29], v[106:107]
	v_pk_mul_f32 v[14:15], v[26:27], v[26:27]
	v_pk_mul_f32 v[16:17], v[28:29], v[28:29]
	v_add_f32_e32 v14, v14, v15
	v_add_f32_e32 v14, v14, v16
	v_add_f32_e32 v14, v14, v17
	v_add_f32_e32 v14, v18, v14
	ds_bpermute_b32 v15, v2, v14
	v_cvt_pk_bf16_f32 v16, v26, v27
	v_cvt_pk_bf16_f32 v17, v28, v29
	global_store_dwordx2 v[30:31], v[16:17], off offset:1536
	s_waitcnt lgkmcnt(0)
	v_add_f32_e32 v14, v14, v15
	ds_bpermute_b32 v15, v8, v14
	s_waitcnt lgkmcnt(0)
	v_add_f32_e32 v14, v14, v15
	ds_bpermute_b32 v15, v9, v14
	s_waitcnt lgkmcnt(0)
	v_add_f32_e32 v14, v14, v15
	ds_bpermute_b32 v15, v10, v14
	s_waitcnt lgkmcnt(0)
	v_add_f32_e32 v14, v14, v15
	ds_bpermute_b32 v15, v11, v14
	s_waitcnt lgkmcnt(0)
	v_add_f32_e32 v14, v14, v15
	ds_bpermute_b32 v15, v12, v14
	s_mov_b64 s[10:11], exec
	v_readlane_b32 s12, v252, 40
	v_readlane_b32 s13, v252, 41
	s_and_b64 s[12:13], s[10:11], s[12:13]
	s_mov_b64 exec, s[12:13]
	s_cbranch_execz .LBB0_1468
	v_readlane_b32 s12, v252, 42
	s_waitcnt lgkmcnt(0)
	v_add_f32_e32 v14, v14, v15
	v_readlane_b32 s13, v252, 43
	s_nop 1
	v_cndmask_b32_e64 v16, 0, v14, s[12:13]
	v_lshl_add_u64 v[14:15], s[94:95], 0, v[6:7]
	global_store_dword v[14:15], v16, off
	s_branch .LBB0_1468
